# P0 silu table: 18 serial load+wait steps replaced by 18 LDS-DMA loads + one wait + in-place LDS pass
# speedup vs baseline: 1.0012x; 1.0012x over previous
; #define LAS __attribute__((address_space(3)))
; __device__ __forceinline__ void p0_prologue(const Args& a, LAS unsigned char* lds, int bid, int G, int tid) {
;     asm volatile("" : "+v"(tid));
;     unsigned char* ws = a.ws;
;     const int wave = tid >> 6, lane = tid & 63;
;     if (bid < 192) {
;         LAS float* sl = (LAS float*)lds;
;         for (int i = tid; i < 9 * 1024; i += 512) { const int r = i >> 10, k = i & 1023; const float v = r < 8 ? a.in[1][r * 1024 + k] : a.in[3][k]; sl[i] = v / (1.f + __expf(-v)); }
;         __syncthreads();
.LBB0_4:
	s_load_dwordx8 s[12:19], s[0:1], 0x80
	s_waitcnt lgkmcnt(0)
	s_add_u32 s4, s60, 0x2e00000
	s_addc_u32 s5, s61, 0
	v_mov_b32_e32 v6, v179
	v_writelane_b32 v252, s12, 0
	v_ashrrev_i32_e32 v3, 6, v6
	s_cmpk_gt_i32 s2, 0xbf
	v_writelane_b32 v252, s13, 1
	v_writelane_b32 v252, s14, 2
	v_writelane_b32 v252, s15, 3
	v_writelane_b32 v252, s16, 4
	v_writelane_b32 v252, s17, 5
	v_writelane_b32 v252, s18, 6
	v_writelane_b32 v252, s19, 7
	s_load_dwordx16 s[16:31], s[0:1], 0x0
	v_writelane_b32 v252, s4, 8
	v_and_b32_e32 v2, 63, v6
	s_nop 0
	v_writelane_b32 v252, s5, 9
	s_cbranch_scc1 .LBB0_20
	s_movk_i32 s4, 0x23ff
	v_cmp_lt_i32_e32 vcc, s4, v6
	v_lshlrev_b32_e32 v1, 2, v6
	s_and_saveexec_b64 s[4:5], vcc
	v_readlane_b32 s10, v252, 8
	s_xor_b64 s[4:5], exec, s[4:5]
	v_readlane_b32 s11, v252, 9
	v_lshlrev_b32_e32 v1, 2, v6
	s_andn2_saveexec_b64 s[4:5], s[4:5]
	s_cbranch_execz .LBB0_11
	s_waitcnt lgkmcnt(0)
	v_mov_b32_e32 v4, s18
	v_mov_b32_e32 v5, s19
	v_ashrrev_i32_e32 v7, 31, v6
	v_add_u32_e32 v10, 0, v1
	v_lshl_add_u64 v[4:5], v[6:7], 2, v[4:5]
	s_mov_b64 s[6:7], 0
	s_movk_i32 s12, 0x2000
	v_mov_b32_e32 v9, 0
	s_mov_b64 s[10:11], 0x800
	s_movk_i32 s13, 0x21ff
	v_mov_b32_e32 v7, v6
	s_lshr_b32 s100, s33, 6
	s_lshl_b32 s100, s100, 8
.LBB0_9:
	v_and_b32_e32 v8, 0x3ff, v7
	v_lshlrev_b32_e32 v8, 2, v8
	v_lshl_add_u64 v[12:13], s[22:23], 0, v[8:9]
	v_cmp_gt_i32_e32 vcc, s12, v7
	v_add_u32_e32 v11, 0x200, v7
	s_nop 0
	v_cndmask_b32_e32 v13, v13, v5, vcc
	v_cndmask_b32_e32 v12, v12, v4, vcc
	s_mov_b32 m0, s100
	s_nop 0
	global_load_lds_dword v[12:13], off
	v_cmp_lt_i32_e32 vcc, s13, v7
	v_mov_b32_e32 v7, v11
	s_or_b64 s[6:7], vcc, s[6:7]
	v_lshl_add_u64 v[4:5], v[4:5], 0, s[10:11]
	s_add_i32 s100, s100, 0x800
	s_andn2_b64 exec, exec, s[6:7]
	s_cbranch_execnz .LBB0_9
	s_or_b64 exec, exec, s[6:7]
	s_waitcnt vmcnt(0)
	s_mov_b32 s100, 0
.Lsilu_b:
	ds_read_b32 v8, v10
	s_waitcnt lgkmcnt(0)
	v_mul_f32_e32 v11, 0xbfb8aa3b, v8
	v_exp_f32_e32 v11, v11
	s_nop 0
	v_add_f32_e32 v11, 1.0, v11
	v_div_scale_f32 v12, s[14:15], v11, v11, v8
	v_rcp_f32_e32 v13, v12
	v_div_scale_f32 v14, vcc, v8, v11, v8
	v_fma_f32 v15, -v12, v13, 1.0
	v_fmac_f32_e32 v13, v15, v13
	v_mul_f32_e32 v15, v14, v13
	v_fma_f32 v16, -v12, v15, v14
	v_fmac_f32_e32 v15, v16, v13
	v_fma_f32 v12, -v12, v15, v14
	v_div_fmas_f32 v12, v12, v13, v15
	v_div_fixup_f32 v8, v12, v11, v8
	ds_write_b32 v10, v8
	v_add_u32_e32 v10, 0x800, v10
	s_add_i32 s100, s100, 1
	s_cmp_lt_u32 s100, 18
	s_cbranch_scc1 .Lsilu_b
	s_or_b64 exec, exec, s[6:7]
	v_readlane_b32 s10, v252, 8
	v_readlane_b32 s11, v252, 9
